# P8: non-temporal F stores for row-tile groups 2,3,4 (j >= 8)
# baseline (speedup 1.0000x reference)
.LBB0_898:
	s_mul_i32 s98, s26, 0xccd
	s_lshr_b32 s98, s98, 16
	s_mul_i32 s98, s98, 20
	s_sub_i32 s98, s26, s98
	s_cmp_ge_u32 s98, 8
	s_cselect_b32 s99, 1, 0
	v_max_f32_e32 v125, v125, v125
	v_max_f32_e32 v124, v124, v124
	v_max_f32_e32 v127, v127, v127
	v_max_f32_e32 v126, v126, v126
	v_max_f32_e32 v121, v121, v121
	v_max_f32_e32 v120, v120, v120
	v_max_f32_e32 v123, v123, v123
	v_max_f32_e32 v122, v122, v122
	v_max_f32_e32 v125, 0, v125
	v_max_f32_e32 v124, 0, v124
	v_max_f32_e32 v127, 0, v127
	v_max_f32_e32 v126, 0, v126
	v_max_f32_e32 v121, 0, v121
	v_max_f32_e32 v120, 0, v120
	v_max_f32_e32 v123, 0, v123
	v_max_f32_e32 v122, 0, v122
	v_pk_mul_f32 v[126:127], v[126:127], v[126:127]
	v_pk_mul_f32 v[124:125], v[124:125], v[124:125]
	v_pk_mul_f32 v[152:153], v[122:123], v[122:123]
	v_pk_mul_f32 v[122:123], v[120:121], v[120:121]
	s_nop 7
	v_cvt_pk_bf16_f32 v120, v124, v125
	v_cvt_pk_bf16_f32 v121, v126, v127
	v_cvt_pk_bf16_f32 v122, v122, v123
	v_cvt_pk_bf16_f32 v123, v152, v153
	v_max_f32_e32 v117, 0, v117
	v_max_f32_e32 v116, 0, v116
	v_max_f32_e32 v119, 0, v119
	v_max_f32_e32 v118, 0, v118
	v_max_f32_e32 v113, 0, v113
	v_max_f32_e32 v112, 0, v112
	v_max_f32_e32 v115, 0, v115
	v_max_f32_e32 v114, 0, v114
	ds_write_b128 v147, v[120:123]
	v_pk_mul_f32 v[118:119], v[118:119], v[118:119]
	v_pk_mul_f32 v[116:117], v[116:117], v[116:117]
	v_pk_mul_f32 v[120:121], v[114:115], v[114:115]
	v_pk_mul_f32 v[114:115], v[112:113], v[112:113]
	v_lshl_add_u32 v150, s26, 8, v143
	v_cvt_pk_bf16_f32 v112, v116, v117
	v_cvt_pk_bf16_f32 v113, v118, v119
	v_cvt_pk_bf16_f32 v114, v114, v115
	v_cvt_pk_bf16_f32 v115, v120, v121
	v_ashrrev_i32_e32 v151, 31, v150
	ds_write_b128 v147, v[112:115] offset:64
	v_lshlrev_b64 v[150:151], 13, v[150:151]
	s_lshl_b32 s28, s61, 8
	ds_read_b128 v[114:117], v148
	ds_read_b128 v[118:121], v148 offset:1152
	v_lshl_add_u64 v[150:151], s[4:5], 0, v[150:151]
	s_ashr_i32 s29, s28, 31
	v_lshl_add_u64 v[112:113], s[28:29], 1, v[150:151]
	v_lshl_add_u64 v[112:113], v[112:113], 0, s[8:9]
	v_lshl_add_u64 v[112:113], v[112:113], 0, v[132:133]
	s_waitcnt lgkmcnt(0)
	s_cmp_lg_u32 s99, 0
	s_cbranch_scc1 .Lf8nt_0
	global_store_dwordx4 v[112:113], v[114:117], off
	s_branch .Lf8d_0
